# scan S^T blocks: 8 K-fragment LDS reads in flight per block with counted lgkmcnt waits (was one read per MFMA)
# speedup vs baseline: 1.0494x; 1.0007x over previous
.LBB0_628:
	s_bitcmp1_b32 s57, 0
	s_cselect_b32 s50, 0x900, 0
	s_add_i32 s61, s50, 0
	s_add_i32 s61, s61, 0x1c800
	s_waitcnt vmcnt(8)
	ds_write_b128 v184, v[4:7]
	s_waitcnt vmcnt(7)
	ds_write_b128 v185, v[8:11]
	s_waitcnt vmcnt(6)
	ds_write_b128 v186, v[12:15]
	s_waitcnt vmcnt(5)
	ds_write_b128 v187, v[16:19]
	s_waitcnt vmcnt(4)
	ds_write_b128 v188, v[20:23]
	s_waitcnt vmcnt(3)
	ds_write_b128 v189, v[24:27]
	s_waitcnt vmcnt(2)
	ds_write_b128 v190, v[28:31]
	s_waitcnt vmcnt(1)
	ds_write_b128 v191, v[32:35]
	v_lshl_add_u32 v1, v160, 2, s61
	ds_read_b32 v2, v1 offset:1536
	s_waitcnt vmcnt(0)
	v_lshlrev_b32_e32 v96, 16, v36
	v_and_b32_e32 v97, 0xffff0000, v36
	ds_write_b16 v165, v36
	ds_write_b16_d16_hi v165, v36 offset:272
	ds_write_b16 v165, v37 offset:544
	ds_write_b16_d16_hi v165, v37 offset:816
	ds_write_b16 v165, v38 offset:1088
	ds_write_b16_d16_hi v165, v38 offset:1360
	ds_write_b16 v165, v39 offset:1632
	ds_write_b16_d16_hi v165, v39 offset:1904
	s_waitcnt lgkmcnt(8)
	v_pk_mul_f32 v[96:97], v[2:3], v[96:97] op_sel_hi:[0,1]
	v_cvt_pk_bf16_f32 v1, v96, v97
	v_lshlrev_b32_e32 v96, 16, v37
	v_and_b32_e32 v97, 0xffff0000, v37
	v_pk_mul_f32 v[96:97], v[2:3], v[96:97] op_sel_hi:[0,1]
	v_cvt_pk_bf16_f32 v3, v96, v97
	v_lshlrev_b32_e32 v96, 16, v38
	v_and_b32_e32 v97, 0xffff0000, v38
	v_pk_mul_f32 v[96:97], v[2:3], v[96:97] op_sel_hi:[0,1]
	v_cvt_pk_bf16_f32 v98, v96, v97
	v_lshlrev_b32_e32 v96, 16, v39
	v_and_b32_e32 v97, 0xffff0000, v39
	v_pk_mul_f32 v[96:97], v[2:3], v[96:97] op_sel_hi:[0,1]
	v_cvt_pk_bf16_f32 v96, v96, v97
	ds_write_b16 v166, v1
	ds_write_b16_d16_hi v166, v1 offset:272
	ds_write_b16 v166, v3 offset:544
	ds_write_b16_d16_hi v166, v3 offset:816
	ds_write_b16 v166, v98 offset:1088
	ds_write_b16_d16_hi v166, v98 offset:1360
	ds_write_b16 v166, v96 offset:1632
	ds_write_b16_d16_hi v166, v96 offset:1904
	s_and_saveexec_b64 s[50:51], s[14:15]
	v_cvt_pk_bf16_f32 v1, v2, s0
	ds_write_b16 v167, v1
	s_or_b64 exec, exec, s[50:51]
	s_cmp_lt_u32 s57, 2
	s_waitcnt lgkmcnt(0)
	s_barrier
	s_cbranch_scc1 .LBB0_655
	v_mov_b32_e32 v96, 0
	v_mov_b32_e32 v100, 0
	v_mov_b32_e32 v101, 0
	v_mov_b32_e32 v102, 0
	v_mov_b32_e32 v103, 0
	s_and_saveexec_b64 s[50:51], s[16:17]
	s_cbranch_execz .LBB0_633
	ds_read_b128 v[98:101], v169
	ds_read_b128 v[102:105], v169 offset:64
	ds_read_b128 v[214:217], v169 offset:128
	ds_read_b128 v[218:221], v169 offset:192
	ds_read_b128 v[236:239], v169 offset:256
	ds_read_b128 v[240:243], v169 offset:320
	ds_read_b128 v[244:247], v169 offset:384
	ds_read_b128 v[248:251], v169 offset:448
	s_waitcnt lgkmcnt(7)
	v_mfma_f32_16x16x32_bf16 v[98:101], v[98:101], v[40:43], 0
	s_waitcnt lgkmcnt(6)
	v_mfma_f32_16x16x32_bf16 v[98:101], v[102:105], v[44:47], v[98:101]
	s_waitcnt lgkmcnt(5)
	v_mfma_f32_16x16x32_bf16 v[98:101], v[214:217], v[48:51], v[98:101]
	s_waitcnt lgkmcnt(4)
	v_mfma_f32_16x16x32_bf16 v[98:101], v[218:221], v[52:55], v[98:101]
	s_waitcnt lgkmcnt(3)
	v_mfma_f32_16x16x32_bf16 v[98:101], v[236:239], v[56:59], v[98:101]
	s_waitcnt lgkmcnt(2)
	v_mfma_f32_16x16x32_bf16 v[98:101], v[240:243], v[60:63], v[98:101]
	s_waitcnt lgkmcnt(1)
	v_mfma_f32_16x16x32_bf16 v[98:101], v[244:247], v[64:67], v[98:101]
	s_waitcnt lgkmcnt(0)
	v_mfma_f32_16x16x32_bf16 v[100:103], v[248:251], v[68:71], v[98:101]
.LBB0_633:
	s_or_b64 exec, exec, s[50:51]
	v_mov_b32_e32 v97, 0
	s_nop 2
	v_mov_b32_e32 v98, 0
	v_mov_b32_e32 v99, 0
	s_and_saveexec_b64 s[50:51], s[18:19]
	s_cbranch_execz .LBB0_635
	ds_read_b128 v[96:99], v169 offset:8448
	ds_read_b128 v[104:107], v169 offset:8512
	ds_read_b128 v[214:217], v169 offset:8576
	ds_read_b128 v[218:221], v169 offset:8640
	ds_read_b128 v[236:239], v169 offset:8704
	ds_read_b128 v[240:243], v169 offset:8768
	ds_read_b128 v[244:247], v169 offset:8832
	ds_read_b128 v[248:251], v169 offset:8896
	s_waitcnt lgkmcnt(7)
	v_mfma_f32_16x16x32_bf16 v[96:99], v[96:99], v[40:43], 0
	s_waitcnt lgkmcnt(6)
	v_mfma_f32_16x16x32_bf16 v[96:99], v[104:107], v[44:47], v[96:99]
	s_waitcnt lgkmcnt(5)
	v_mfma_f32_16x16x32_bf16 v[96:99], v[214:217], v[48:51], v[96:99]
	s_waitcnt lgkmcnt(4)
	v_mfma_f32_16x16x32_bf16 v[96:99], v[218:221], v[52:55], v[96:99]
	s_waitcnt lgkmcnt(3)
	v_mfma_f32_16x16x32_bf16 v[96:99], v[236:239], v[56:59], v[96:99]
	s_waitcnt lgkmcnt(2)
	v_mfma_f32_16x16x32_bf16 v[96:99], v[240:243], v[60:63], v[96:99]
	s_waitcnt lgkmcnt(1)
	v_mfma_f32_16x16x32_bf16 v[96:99], v[244:247], v[64:67], v[96:99]
	s_waitcnt lgkmcnt(0)
	v_mfma_f32_16x16x32_bf16 v[96:99], v[248:251], v[68:71], v[96:99]
.LBB0_635:
	s_or_b64 exec, exec, s[50:51]
	v_mov_b32_e32 v104, 0
	v_mov_b32_e32 v108, 0
	v_mov_b32_e32 v109, 0
	v_mov_b32_e32 v110, 0
	v_mov_b32_e32 v111, 0
	s_and_saveexec_b64 s[50:51], s[20:21]
	s_cbranch_execz .LBB0_637
	ds_read_b128 v[106:109], v169 offset:16896
	ds_read_b128 v[110:113], v169 offset:16960
	ds_read_b128 v[214:217], v169 offset:17024
	ds_read_b128 v[218:221], v169 offset:17088
	ds_read_b128 v[236:239], v169 offset:17152
	ds_read_b128 v[240:243], v169 offset:17216
	ds_read_b128 v[244:247], v169 offset:17280
	ds_read_b128 v[248:251], v169 offset:17344
	s_waitcnt lgkmcnt(7)
	v_mfma_f32_16x16x32_bf16 v[106:109], v[106:109], v[40:43], 0
	s_waitcnt lgkmcnt(6)
	v_mfma_f32_16x16x32_bf16 v[106:109], v[110:113], v[44:47], v[106:109]
	s_waitcnt lgkmcnt(5)
	v_mfma_f32_16x16x32_bf16 v[106:109], v[214:217], v[48:51], v[106:109]
	s_waitcnt lgkmcnt(4)
	v_mfma_f32_16x16x32_bf16 v[106:109], v[218:221], v[52:55], v[106:109]
	s_waitcnt lgkmcnt(3)
	v_mfma_f32_16x16x32_bf16 v[106:109], v[236:239], v[56:59], v[106:109]
	s_waitcnt lgkmcnt(2)
	v_mfma_f32_16x16x32_bf16 v[106:109], v[240:243], v[60:63], v[106:109]
	s_waitcnt lgkmcnt(1)
	v_mfma_f32_16x16x32_bf16 v[106:109], v[244:247], v[64:67], v[106:109]
	s_waitcnt lgkmcnt(0)
	v_mfma_f32_16x16x32_bf16 v[108:111], v[248:251], v[68:71], v[106:109]
.LBB0_637:
	s_or_b64 exec, exec, s[50:51]
	v_mov_b32_e32 v105, 0
	s_nop 2
	v_mov_b32_e32 v106, 0
	v_mov_b32_e32 v107, 0
	s_and_saveexec_b64 s[50:51], s[22:23]
	s_cbranch_execz .LBB0_639
	ds_read_b128 v[104:107], v169 offset:25344
	ds_read_b128 v[112:115], v169 offset:25408
	ds_read_b128 v[214:217], v169 offset:25472
	ds_read_b128 v[218:221], v169 offset:25536
	ds_read_b128 v[236:239], v169 offset:25600
	ds_read_b128 v[240:243], v169 offset:25664
	ds_read_b128 v[244:247], v169 offset:25728
	ds_read_b128 v[248:251], v169 offset:25792
	s_waitcnt lgkmcnt(7)
	v_mfma_f32_16x16x32_bf16 v[104:107], v[104:107], v[40:43], 0
	s_waitcnt lgkmcnt(6)
	v_mfma_f32_16x16x32_bf16 v[104:107], v[112:115], v[44:47], v[104:107]
	s_waitcnt lgkmcnt(5)
	v_mfma_f32_16x16x32_bf16 v[104:107], v[214:217], v[48:51], v[104:107]
	s_waitcnt lgkmcnt(4)
	v_mfma_f32_16x16x32_bf16 v[104:107], v[218:221], v[52:55], v[104:107]
	s_waitcnt lgkmcnt(3)
	v_mfma_f32_16x16x32_bf16 v[104:107], v[236:239], v[56:59], v[104:107]
	s_waitcnt lgkmcnt(2)
	v_mfma_f32_16x16x32_bf16 v[104:107], v[240:243], v[60:63], v[104:107]
	s_waitcnt lgkmcnt(1)
	v_mfma_f32_16x16x32_bf16 v[104:107], v[244:247], v[64:67], v[104:107]
	s_waitcnt lgkmcnt(0)
	v_mfma_f32_16x16x32_bf16 v[104:107], v[248:251], v[68:71], v[104:107]
.LBB0_639:
	s_or_b64 exec, exec, s[50:51]
	v_mov_b32_e32 v112, 0
	v_mov_b32_e32 v116, 0
	v_mov_b32_e32 v117, 0
	v_mov_b32_e32 v118, 0
	v_mov_b32_e32 v119, 0
	s_and_saveexec_b64 s[50:51], s[24:25]
	s_cbranch_execz .LBB0_641
	ds_read_b128 v[114:117], v169 offset:33792
	ds_read_b128 v[118:121], v169 offset:33856
	ds_read_b128 v[214:217], v169 offset:33920
	ds_read_b128 v[218:221], v169 offset:33984
	ds_read_b128 v[236:239], v169 offset:34048
	ds_read_b128 v[240:243], v169 offset:34112
	ds_read_b128 v[244:247], v169 offset:34176
	ds_read_b128 v[248:251], v169 offset:34240
	s_waitcnt lgkmcnt(7)
	v_mfma_f32_16x16x32_bf16 v[114:117], v[114:117], v[40:43], 0
	s_waitcnt lgkmcnt(6)
	v_mfma_f32_16x16x32_bf16 v[114:117], v[118:121], v[44:47], v[114:117]
	s_waitcnt lgkmcnt(5)
	v_mfma_f32_16x16x32_bf16 v[114:117], v[214:217], v[48:51], v[114:117]
	s_waitcnt lgkmcnt(4)
	v_mfma_f32_16x16x32_bf16 v[114:117], v[218:221], v[52:55], v[114:117]
	s_waitcnt lgkmcnt(3)
	v_mfma_f32_16x16x32_bf16 v[114:117], v[236:239], v[56:59], v[114:117]
	s_waitcnt lgkmcnt(2)
	v_mfma_f32_16x16x32_bf16 v[114:117], v[240:243], v[60:63], v[114:117]
	s_waitcnt lgkmcnt(1)
	v_mfma_f32_16x16x32_bf16 v[114:117], v[244:247], v[64:67], v[114:117]
	s_waitcnt lgkmcnt(0)
	v_mfma_f32_16x16x32_bf16 v[116:119], v[248:251], v[68:71], v[114:117]
.LBB0_641:
	s_or_b64 exec, exec, s[50:51]
	v_mov_b32_e32 v113, 0
	s_nop 2
	v_mov_b32_e32 v114, 0
	v_mov_b32_e32 v115, 0
	s_and_saveexec_b64 s[50:51], s[26:27]
	s_cbranch_execz .LBB0_643
	ds_read_b128 v[112:115], v169 offset:42240
	ds_read_b128 v[120:123], v169 offset:42304
	ds_read_b128 v[214:217], v169 offset:42368
	ds_read_b128 v[218:221], v169 offset:42432
	ds_read_b128 v[236:239], v169 offset:42496
	ds_read_b128 v[240:243], v169 offset:42560
	ds_read_b128 v[244:247], v169 offset:42624
	ds_read_b128 v[248:251], v169 offset:42688
	s_waitcnt lgkmcnt(7)
	v_mfma_f32_16x16x32_bf16 v[112:115], v[112:115], v[40:43], 0
	s_waitcnt lgkmcnt(6)
	v_mfma_f32_16x16x32_bf16 v[112:115], v[120:123], v[44:47], v[112:115]
	s_waitcnt lgkmcnt(5)
	v_mfma_f32_16x16x32_bf16 v[112:115], v[214:217], v[48:51], v[112:115]
	s_waitcnt lgkmcnt(4)
	v_mfma_f32_16x16x32_bf16 v[112:115], v[218:221], v[52:55], v[112:115]
	s_waitcnt lgkmcnt(3)
	v_mfma_f32_16x16x32_bf16 v[112:115], v[236:239], v[56:59], v[112:115]
	s_waitcnt lgkmcnt(2)
	v_mfma_f32_16x16x32_bf16 v[112:115], v[240:243], v[60:63], v[112:115]
	s_waitcnt lgkmcnt(1)
	v_mfma_f32_16x16x32_bf16 v[112:115], v[244:247], v[64:67], v[112:115]
	s_waitcnt lgkmcnt(0)
	v_mfma_f32_16x16x32_bf16 v[112:115], v[248:251], v[68:71], v[112:115]
.LBB0_643:
	s_or_b64 exec, exec, s[50:51]
	v_mov_b32_e32 v120, 0
	v_mov_b32_e32 v124, 0
	v_mov_b32_e32 v125, 0
	v_mov_b32_e32 v126, 0
	v_mov_b32_e32 v127, 0
	s_and_saveexec_b64 s[50:51], s[28:29]
	s_cbranch_execz .LBB0_645
	ds_read_b128 v[122:125], v169 offset:50688
	ds_read_b128 v[126:129], v169 offset:50752
	ds_read_b128 v[214:217], v169 offset:50816
	ds_read_b128 v[218:221], v169 offset:50880
	ds_read_b128 v[236:239], v169 offset:50944
	ds_read_b128 v[240:243], v169 offset:51008
	ds_read_b128 v[244:247], v169 offset:51072
	ds_read_b128 v[248:251], v169 offset:51136
	s_waitcnt lgkmcnt(7)
	v_mfma_f32_16x16x32_bf16 v[122:125], v[122:125], v[40:43], 0
	s_waitcnt lgkmcnt(6)
	v_mfma_f32_16x16x32_bf16 v[122:125], v[126:129], v[44:47], v[122:125]
	s_waitcnt lgkmcnt(5)
	v_mfma_f32_16x16x32_bf16 v[122:125], v[214:217], v[48:51], v[122:125]
	s_waitcnt lgkmcnt(4)
	v_mfma_f32_16x16x32_bf16 v[122:125], v[218:221], v[52:55], v[122:125]
	s_waitcnt lgkmcnt(3)
	v_mfma_f32_16x16x32_bf16 v[122:125], v[236:239], v[56:59], v[122:125]
	s_waitcnt lgkmcnt(2)
	v_mfma_f32_16x16x32_bf16 v[122:125], v[240:243], v[60:63], v[122:125]
	s_waitcnt lgkmcnt(1)
	v_mfma_f32_16x16x32_bf16 v[122:125], v[244:247], v[64:67], v[122:125]
	s_waitcnt lgkmcnt(0)
	v_mfma_f32_16x16x32_bf16 v[124:127], v[248:251], v[68:71], v[122:125]
.LBB0_645:
	s_or_b64 exec, exec, s[50:51]
	v_mov_b32_e32 v121, 0
	s_nop 2
	v_mov_b32_e32 v122, 0
	v_mov_b32_e32 v123, 0
	s_and_saveexec_b64 s[50:51], s[30:31]
	s_cbranch_execz .LBB0_647
	ds_read_b128 v[120:123], v169 offset:59136
	ds_read_b128 v[128:131], v169 offset:59200
	ds_read_b128 v[214:217], v169 offset:59264
	ds_read_b128 v[218:221], v169 offset:59328
	ds_read_b128 v[236:239], v169 offset:59392
	ds_read_b128 v[240:243], v169 offset:59456
	ds_read_b128 v[244:247], v169 offset:59520
	ds_read_b128 v[248:251], v169 offset:59584
	s_waitcnt lgkmcnt(7)
	v_mfma_f32_16x16x32_bf16 v[120:123], v[120:123], v[40:43], 0
	s_waitcnt lgkmcnt(6)
	v_mfma_f32_16x16x32_bf16 v[120:123], v[128:131], v[44:47], v[120:123]
	s_waitcnt lgkmcnt(5)
	v_mfma_f32_16x16x32_bf16 v[120:123], v[214:217], v[48:51], v[120:123]
	s_waitcnt lgkmcnt(4)
	v_mfma_f32_16x16x32_bf16 v[120:123], v[218:221], v[52:55], v[120:123]
	s_waitcnt lgkmcnt(3)
	v_mfma_f32_16x16x32_bf16 v[120:123], v[236:239], v[56:59], v[120:123]
	s_waitcnt lgkmcnt(2)
	v_mfma_f32_16x16x32_bf16 v[120:123], v[240:243], v[60:63], v[120:123]
	s_waitcnt lgkmcnt(1)
	v_mfma_f32_16x16x32_bf16 v[120:123], v[244:247], v[64:67], v[120:123]
	s_waitcnt lgkmcnt(0)
	v_mfma_f32_16x16x32_bf16 v[120:123], v[248:251], v[68:71], v[120:123]
